# v79_a1_mfma_A_operand_from_global_no_lds_stage
# baseline (speedup 1.0000x reference)
; #define LAS __attribute__((address_space(3)))
; __device__ __forceinline__ void gla_bcum(KArgs a, int tid, int t0, int h, LAS float* segtot, LAS float* glrs, float (&bc)[32], float& tot) {
;     ...
;     for (int j = 0; j < 16; ++j) w2r[j] = a->gate_w2[j * 512 + col];
;     const float bias = a->gate_b[col];
;     *(LAS f32x4*)(glrs + tid * 4) = *(const f32x4*)(glr + (size_t)t0 * 16 + tid * 4);
;     __syncthreads();
;     float run = 0.f;
; #pragma unroll
;     for (int r = 0; r < 32; ++r) { const LAS f32x4* gp = (const LAS f32x4*)(glrs + (seg * 32 + r) * 16);
;         float z = bias;
; #pragma unroll
;         for (int q = 0; q < 4; ++q) { const f32x4 g = gp[q]; z += g[0] * w2r[4 * q] + g[1] * w2r[4 * q + 1] + g[2] * w2r[4 * q + 2] + g[3] * w2r[4 * q + 3]; }
.LBB0_341:
	s_bfe_u32 s5, s10, 0x20005
	v_lshlrev_b32_e32 v2, 2, v8
	v_lshl_or_b32 v2, s5, 9, v2
	s_and_b32 s0, s2, 0xfffff000
	s_and_b32 s1, s3, 0xf80
	s_or_b32 s20, s0, s1
	s_nop 0
	s_nop 0
	s_ashr_i32 s21, s20, 31
	s_lshl_b64 s[0:1], s[20:21], 6
	s_nop 0
	v_lshl_add_u64 v[16:17], v[10:11], 0, s[0:1]
	s_barrier
	v_lshrrev_b32_e32 v184, 7, v186
	v_and_b32_e32 v185, 31, v186
	v_lshl_or_b32 v184, v184, 5, v185
	v_lshlrev_b32_e32 v184, 6, v184
	v_bfe_u32 v185, v186, 5, 1
	v_lshl_add_u32 v184, v185, 2, v184
	v_lshlrev_b32_e32 v185, 4, v186
	v_sub_u32_e32 v184, v184, v185
	v_ashrrev_i32_e32 v185, 31, v184
	v_lshl_add_u64 v[240:241], v[184:185], 0, v[16:17]
	global_load_dword v176, v[240:241], off
	global_load_dword v177, v[240:241], off offset:8
	global_load_dword v178, v[240:241], off offset:16
	global_load_dword v179, v[240:241], off offset:24
	global_load_dword v180, v[240:241], off offset:32
	global_load_dword v181, v[240:241], off offset:40
	global_load_dword v182, v[240:241], off offset:48
	global_load_dword v183, v[240:241], off offset:56
	s_mul_i32 s98, s5, 0x200
	v_and_b32_e32 v184, 31, v8
	v_and_b32_e32 v185, 64, v8
	v_or_b32_e32 v184, v184, v185
	v_bfe_u32 v185, v8, 5, 1
	v_lshlrev_b32_e32 v184, 2, v184
	v_lshl_add_u32 v184, v185, 11, v184
	v_add_u32_e32 v184, s98, v184
	global_load_dword v224, v184, s[12:13]
	global_load_dword v225, v184, s[12:13] offset:128
	v_add_u32_e32 v184, 0x1000, v184
	global_load_dword v226, v184, s[12:13]
	global_load_dword v227, v184, s[12:13] offset:128
	v_add_u32_e32 v184, 0x1000, v184
	global_load_dword v228, v184, s[12:13]
	global_load_dword v229, v184, s[12:13] offset:128
	v_add_u32_e32 v184, 0x1000, v184
	global_load_dword v230, v184, s[12:13]
	global_load_dword v231, v184, s[12:13] offset:128
	v_add_u32_e32 v184, 0x1000, v184
	global_load_dword v232, v184, s[12:13]
	global_load_dword v233, v184, s[12:13] offset:128
	v_add_u32_e32 v184, 0x1000, v184
	global_load_dword v234, v184, s[12:13]
	global_load_dword v235, v184, s[12:13] offset:128
	v_add_u32_e32 v184, 0x1000, v184
	global_load_dword v236, v184, s[12:13]
	global_load_dword v237, v184, s[12:13] offset:128
	v_add_u32_e32 v184, 0x1000, v184
	global_load_dword v238, v184, s[12:13]
	global_load_dword v239, v184, s[12:13] offset:128
	s_nop 0
	s_nop 0
	s_nop 0
	s_nop 0
	s_nop 0
	v_readfirstlane_b32 s1, v32
	s_nop 0
	s_nop 0
	s_nop 0
	s_nop 0
	s_nop 0
	global_load_dword v2, v2, s[14:15]
	s_ashr_i32 s0, s1, 7
	s_lshl_b32 s6, s0, 11
	s_add_i32 s6, s6, 0
	v_mov_b32_e32 v42, s6
	s_and_b32 s1, s1, 0x3fffff80
	s_cmp_gt_i32 s0, 0
	s_waitcnt vmcnt(16)
	v_mfma_f32_32x32x2_f32 v[144:159], v176, v224, 0
	s_waitcnt vmcnt(15)
	v_mfma_f32_32x32x2_f32 v[160:175], v176, v225, 0
	s_waitcnt vmcnt(14)
	v_mfma_f32_32x32x2_f32 v[144:159], v177, v226, v[144:159]
	s_waitcnt vmcnt(13)
	v_mfma_f32_32x32x2_f32 v[160:175], v177, v227, v[160:175]
	s_waitcnt vmcnt(12)
	v_mfma_f32_32x32x2_f32 v[144:159], v178, v228, v[144:159]
	s_waitcnt vmcnt(11)
	v_mfma_f32_32x32x2_f32 v[160:175], v178, v229, v[160:175]
	s_waitcnt vmcnt(10)
	v_mfma_f32_32x32x2_f32 v[144:159], v179, v230, v[144:159]
	s_waitcnt vmcnt(9)
	v_mfma_f32_32x32x2_f32 v[160:175], v179, v231, v[160:175]
	s_waitcnt vmcnt(8)
	v_mfma_f32_32x32x2_f32 v[144:159], v180, v232, v[144:159]
	s_waitcnt vmcnt(7)
	v_mfma_f32_32x32x2_f32 v[160:175], v180, v233, v[160:175]
	s_waitcnt vmcnt(6)
	v_mfma_f32_32x32x2_f32 v[144:159], v181, v234, v[144:159]
	s_waitcnt vmcnt(5)
	v_mfma_f32_32x32x2_f32 v[160:175], v181, v235, v[160:175]
	s_waitcnt vmcnt(4)
	v_mfma_f32_32x32x2_f32 v[144:159], v182, v236, v[144:159]
	s_waitcnt vmcnt(3)
	v_mfma_f32_32x32x2_f32 v[160:175], v182, v237, v[160:175]
	s_waitcnt vmcnt(2)
	v_mfma_f32_32x32x2_f32 v[144:159], v183, v238, v[144:159]
	s_waitcnt vmcnt(1)
	v_mfma_f32_32x32x2_f32 v[160:175], v183, v239, v[160:175]
	s_nop 15
	s_nop 3
	v_permlane32_swap_b32_e32 v144, v160
	v_permlane32_swap_b32_e32 v145, v161
	v_permlane32_swap_b32_e32 v146, v162
	v_permlane32_swap_b32_e32 v147, v163
	v_permlane32_swap_b32_e32 v148, v164
	v_permlane32_swap_b32_e32 v149, v165
	v_permlane32_swap_b32_e32 v150, v166
	v_permlane32_swap_b32_e32 v151, v167
	v_permlane32_swap_b32_e32 v152, v168
	v_permlane32_swap_b32_e32 v153, v169
	v_permlane32_swap_b32_e32 v154, v170
	v_permlane32_swap_b32_e32 v155, v171
	v_permlane32_swap_b32_e32 v156, v172
	v_permlane32_swap_b32_e32 v157, v173
	v_permlane32_swap_b32_e32 v158, v174
	v_permlane32_swap_b32_e32 v159, v175
	s_waitcnt vmcnt(0)
; #define LAS __attribute__((address_space(3)))
; __device__ __forceinline__ float bf2f(bf16_t v) { return __uint_as_float((unsigned)v << 16); }
; __device__ __forceinline__ void gla_bcum(KArgs a, int tid, int t0, int h, LAS float* segtot, LAS float* glrs, float (&bc)[32], float& tot) {
;     ...
;     const float bias = a->gate_b[col];
;     *(LAS f32x4*)(glrs + tid * 4) = *(const f32x4*)(glr + (size_t)t0 * 16 + tid * 4);
;     __syncthreads();
;     float run = 0.f;
; #pragma unroll
;     for (int r = 0; r < 32; ++r) { const LAS f32x4* gp = (const LAS f32x4*)(glrs + (seg * 32 + r) * 16);
;         float z = bias;
; #pragma unroll
;         for (int q = 0; q < 4; ++q) { const f32x4 g = gp[q]; z += g[0] * w2r[4 * q] + g[1] * w2r[4 * q + 1] + g[2] * w2r[4 * q + 2] + g[3] * w2r[4 * q + 3]; }
;         const float la = (fminf(z, 0.f) - __logf(1.0f + __expf(-fabsf(z)))) * (1.0f / 16.0f);
;         run += la; bc[r] = run; }
; __device__ __forceinline__ void gla_a1(const Ctx& X, KArgs a, float* kvt, float* decb) {
;     ...
;               for (int e = 0; e < 8; ++e) { const int r = r8 * 8 + e; kd[e] = bf2f(proj[(size_t)(t0 + seg * 32 + r) * NMAIN + C_GK + h * 128 + d]) * __expf(tot - bc[r]); }
	v_add_f32_e32 v144, v2, v144
	v_add_f32_e32 v160, v2, v160
	v_add_f32_e32 v145, v2, v145
	v_add_f32_e32 v161, v2, v161
	v_add_f32_e32 v146, v2, v146
	v_add_f32_e32 v162, v2, v162
	v_add_f32_e32 v147, v2, v147
	v_add_f32_e32 v163, v2, v163
	v_add_f32_e32 v148, v2, v148
	v_add_f32_e32 v164, v2, v164
	v_add_f32_e32 v149, v2, v149
	v_add_f32_e32 v165, v2, v165
	v_add_f32_e32 v150, v2, v150
	v_add_f32_e32 v166, v2, v166
	v_add_f32_e32 v151, v2, v151
	v_add_f32_e32 v167, v2, v167
	v_add_f32_e32 v152, v2, v152
	v_add_f32_e32 v168, v2, v168
	v_add_f32_e32 v153, v2, v153
	v_add_f32_e32 v169, v2, v169
	v_add_f32_e32 v154, v2, v154
	v_add_f32_e32 v170, v2, v170
	v_add_f32_e32 v155, v2, v155
	v_add_f32_e32 v171, v2, v171
	v_add_f32_e32 v156, v2, v156
	v_add_f32_e32 v172, v2, v172
	v_add_f32_e32 v157, v2, v157
	v_add_f32_e32 v173, v2, v173
	v_add_f32_e32 v158, v2, v158
	v_add_f32_e32 v174, v2, v174
	v_add_f32_e32 v159, v2, v159
	v_add_f32_e32 v175, v2, v175
	v_add_u32_e32 v178, s20, v35
	v_mov_b64_e32 v[176:177], s[18:19]
	v_mad_i64_i32 v[176:177], s[100:101], v178, s35, v[176:177]
	s_mul_i32 s98, s5, 0x100
	s_mov_b32 s99, 0
	v_lshl_add_u64 v[176:177], v[176:177], 0, s[98:99]
	v_lshlrev_b32_e32 v178, 1, v8
	v_mov_b32_e32 v179, 0
	v_lshl_add_u64 v[176:177], v[176:177], 0, v[178:179]
	s_movk_i32 s98, 0x2a00
	global_load_ushort v192, v[176:177], off offset:1024
	v_lshl_add_u64 v[176:177], v[176:177], 0, s[98:99]
	global_load_ushort v193, v[176:177], off offset:1024
	v_lshl_add_u64 v[176:177], v[176:177], 0, s[98:99]
	global_load_ushort v194, v[176:177], off offset:1024
	v_lshl_add_u64 v[176:177], v[176:177], 0, s[98:99]
	global_load_ushort v195, v[176:177], off offset:1024
	v_lshl_add_u64 v[176:177], v[176:177], 0, s[98:99]
	global_load_ushort v196, v[176:177], off offset:1024
	v_lshl_add_u64 v[176:177], v[176:177], 0, s[98:99]
	global_load_ushort v197, v[176:177], off offset:1024
	v_lshl_add_u64 v[176:177], v[176:177], 0, s[98:99]
	global_load_ushort v198, v[176:177], off offset:1024
	v_lshl_add_u64 v[176:177], v[176:177], 0, s[98:99]
	global_load_ushort v199, v[176:177], off offset:1024
	v_lshl_add_u64 v[176:177], v[176:177], 0, s[98:99]
	global_load_ushort v200, v[176:177], off offset:1024
	v_lshl_add_u64 v[176:177], v[176:177], 0, s[98:99]
	global_load_ushort v201, v[176:177], off offset:1024
	v_lshl_add_u64 v[176:177], v[176:177], 0, s[98:99]
	global_load_ushort v202, v[176:177], off offset:1024
	v_lshl_add_u64 v[176:177], v[176:177], 0, s[98:99]
	global_load_ushort v203, v[176:177], off offset:1024
	v_lshl_add_u64 v[176:177], v[176:177], 0, s[98:99]
	global_load_ushort v204, v[176:177], off offset:1024
	v_lshl_add_u64 v[176:177], v[176:177], 0, s[98:99]
	global_load_ushort v205, v[176:177], off offset:1024
	v_lshl_add_u64 v[176:177], v[176:177], 0, s[98:99]
	global_load_ushort v206, v[176:177], off offset:1024
	v_lshl_add_u64 v[176:177], v[176:177], 0, s[98:99]
	global_load_ushort v207, v[176:177], off offset:1024
	v_lshl_add_u64 v[176:177], v[176:177], 0, s[98:99]
	global_load_ushort v208, v[176:177], off offset:1024
	v_lshl_add_u64 v[176:177], v[176:177], 0, s[98:99]
	global_load_ushort v209, v[176:177], off offset:1024
	v_lshl_add_u64 v[176:177], v[176:177], 0, s[98:99]
	global_load_ushort v210, v[176:177], off offset:1024
	v_lshl_add_u64 v[176:177], v[176:177], 0, s[98:99]
	global_load_ushort v211, v[176:177], off offset:1024
	v_lshl_add_u64 v[176:177], v[176:177], 0, s[98:99]
	global_load_ushort v212, v[176:177], off offset:1024
	v_lshl_add_u64 v[176:177], v[176:177], 0, s[98:99]
	global_load_ushort v213, v[176:177], off offset:1024
	v_lshl_add_u64 v[176:177], v[176:177], 0, s[98:99]
	global_load_ushort v214, v[176:177], off offset:1024
	v_lshl_add_u64 v[176:177], v[176:177], 0, s[98:99]
	global_load_ushort v215, v[176:177], off offset:1024
	v_lshl_add_u64 v[176:177], v[176:177], 0, s[98:99]
	global_load_ushort v216, v[176:177], off offset:1024
	v_lshl_add_u64 v[176:177], v[176:177], 0, s[98:99]
	global_load_ushort v217, v[176:177], off offset:1024
	v_lshl_add_u64 v[176:177], v[176:177], 0, s[98:99]
	global_load_ushort v218, v[176:177], off offset:1024
	v_lshl_add_u64 v[176:177], v[176:177], 0, s[98:99]
	global_load_ushort v219, v[176:177], off offset:1024
	v_lshl_add_u64 v[176:177], v[176:177], 0, s[98:99]
	global_load_ushort v220, v[176:177], off offset:1024
	v_lshl_add_u64 v[176:177], v[176:177], 0, s[98:99]
	global_load_ushort v221, v[176:177], off offset:1024
	v_lshl_add_u64 v[176:177], v[176:177], 0, s[98:99]
	global_load_ushort v222, v[176:177], off offset:1024
	v_lshl_add_u64 v[176:177], v[176:177], 0, s[98:99]
	global_load_ushort v223, v[176:177], off offset:1024
	v_mul_f32_e64 v43, |v144|, s4
	v_exp_f32_e32 v43, v43
	s_nop 0
	v_add_f32_e32 v43, 1.0, v43
	v_min_f32_e32 v13, 0, v144
	s_nop 0
	v_log_f32_e32 v43, v43
	s_nop 0
	v_mul_f32_e32 v46, 0x3f317217, v43
	v_fma_f32 v54, v43, s36, -v46
	v_fmac_f32_e32 v54, 0x3377d1cf, v43
	v_fmac_f32_e32 v54, 0x3f317217, v43
	v_mul_f32_e64 v44, |v145|, s4
	v_exp_f32_e32 v44, v44
	v_mov_b32_e32 v43, v54
	v_add_f32_e32 v44, 1.0, v44
	v_sub_f32_e32 v13, v13, v43
	s_mov_b32 s8, 0x3d800000
	v_log_f32_e32 v58, v44
	v_fma_f32 v44, v13, s8, 0
	v_min_f32_e32 v13, 0, v145
	v_mul_f32_e32 v43, 0x3f317217, v58
	v_fma_f32 v43, v58, s36, -v43
	v_mul_f32_e64 v46, |v146|, s4
	v_exp_f32_e32 v46, v46
	v_fmac_f32_e32 v43, 0x3377d1cf, v58
	v_fmac_f32_e32 v43, 0x3f317217, v58
	v_mov_b32_e32 v43, v43
	v_add_f32_e32 v46, 1.0, v46
	v_sub_f32_e32 v13, v13, v43
	v_log_f32_e32 v47, v46
	v_fmamk_f32 v46, v13, 0x3d800000, v44
	v_min_f32_e32 v13, 0, v146
	v_mul_f32_e32 v43, 0x3f317217, v47
	v_fma_f32 v43, v47, s36, -v43
; __device__ __forceinline__ void gla_bcum(KArgs a, int tid, int t0, int h, LAS float* segtot, LAS float* glrs, float (&bc)[32], float& tot) {
;     ...
;         const float la = (fminf(z, 0.f) - __logf(1.0f + __expf(-fabsf(z)))) * (1.0f / 16.0f);
;         run += la; bc[r] = run; }
	v_mul_f32_e64 v48, |v147|, s4
	v_exp_f32_e32 v48, v48
	v_fmac_f32_e32 v43, 0x3377d1cf, v47
	v_fmac_f32_e32 v43, 0x3f317217, v47
	s_nop 1
	v_mov_b32_e32 v43, v43
	v_add_f32_e32 v47, 1.0, v48
	v_sub_f32_e32 v13, v13, v43
	v_min_f32_e32 v43, 0, v147
	v_log_f32_e32 v47, v47
	v_fmamk_f32 v13, v13, 0x3d800000, v46
	v_mul_f32_e32 v45, 0x3f317217, v47
	v_fma_f32 v45, v47, s36, -v45
	v_fmac_f32_e32 v45, 0x3377d1cf, v47
	v_mul_f32_e64 v49, |v160|, s4
	v_exp_f32_e32 v49, v49
	v_fmac_f32_e32 v45, 0x3f317217, v47
	s_nop 1
	v_mov_b32_e32 v45, v45
	v_add_f32_e32 v47, 1.0, v49
	v_sub_f32_e32 v43, v43, v45
	v_min_f32_e32 v45, 0, v160
	v_log_f32_e32 v47, v47
	v_fmamk_f32 v43, v43, 0x3d800000, v13
	v_mul_f32_e32 v56, 0x3f317217, v47
	v_fma_f32 v60, v47, s36, -v56
	v_fmac_f32_e32 v60, 0x3377d1cf, v47
	v_fmac_f32_e32 v60, 0x3f317217, v47
	v_mul_f32_e64 v49, |v161|, s4
	v_exp_f32_e32 v49, v49
	v_mov_b32_e32 v47, v60
	v_add_f32_e32 v49, 1.0, v49
	v_sub_f32_e32 v45, v45, v47
	v_min_f32_e32 v47, 0, v161
	v_log_f32_e32 v60, v49
	v_fmamk_f32 v45, v45, 0x3d800000, v43
	v_mul_f32_e32 v56, 0x3f317217, v60
	v_fma_f32 v61, v60, s36, -v56
	v_fmac_f32_e32 v61, 0x3377d1cf, v60
	v_fmac_f32_e32 v61, 0x3f317217, v60
	v_mul_f32_e64 v49, |v162|, s4
	v_exp_f32_e32 v49, v49
	v_mov_b32_e32 v50, v61
	v_add_f32_e32 v49, 1.0, v49
	v_sub_f32_e32 v47, v47, v50
	v_min_f32_e32 v61, 0, v162
	v_log_f32_e32 v60, v49
	v_fmamk_f32 v47, v47, 0x3d800000, v45
	v_mul_f32_e32 v56, 0x3f317217, v60
	v_fma_f32 v62, v60, s36, -v56
	v_fmac_f32_e32 v62, 0x3377d1cf, v60
	v_fmac_f32_e32 v62, 0x3f317217, v60
	v_mul_f32_e64 v48, |v163|, s4
	v_exp_f32_e32 v48, v48
	v_mov_b32_e32 v50, v62
	v_add_f32_e32 v48, 1.0, v48
	v_min_f32_e32 v49, 0, v163
	s_nop 0
	v_log_f32_e32 v62, v48
	v_sub_f32_e32 v48, v61, v50
	v_fmamk_f32 v48, v48, 0x3d800000, v47
	v_mul_f32_e32 v58, 0x3f317217, v62
	v_fma_f32 v63, v62, s36, -v58
	v_fmac_f32_e32 v63, 0x3377d1cf, v62
	v_fmac_f32_e32 v63, 0x3f317217, v62
	v_mul_f32_e64 v51, |v148|, s4
	v_exp_f32_e32 v51, v51
	s_nop 0
	v_add_f32_e32 v51, 1.0, v51
	v_mov_b32_e32 v52, v63
	v_min_f32_e32 v63, 0, v148
	v_log_f32_e32 v62, v51
	v_mov_b32_e32 v51, v52
	v_sub_f32_e32 v49, v49, v51
	v_mul_f32_e32 v58, 0x3f317217, v62
	v_fma_f32 v64, v62, s36, -v58
	v_fmac_f32_e32 v64, 0x3377d1cf, v62
	v_fmac_f32_e32 v64, 0x3f317217, v62
	v_mul_f32_e64 v50, |v149|, s4
	v_exp_f32_e32 v50, v50
	v_mov_b32_e32 v52, v64
	v_min_f32_e32 v51, 0, v149
	v_add_f32_e32 v50, 1.0, v50
	s_nop 1
	v_log_f32_e32 v64, v50
	v_mov_b32_e32 v50, v52
	v_sub_f32_e32 v50, v63, v50
	v_mul_f32_e32 v60, 0x3f317217, v64
	v_fma_f32 v65, v64, s36, -v60
	v_fmac_f32_e32 v65, 0x3377d1cf, v64
	v_fmac_f32_e32 v65, 0x3f317217, v64
	v_mul_f32_e64 v53, |v150|, s4
	v_exp_f32_e32 v53, v53
	s_nop 0
	v_add_f32_e32 v53, 1.0, v53
	v_mov_b32_e32 v54, v65
	v_min_f32_e32 v65, 0, v150
	v_log_f32_e32 v64, v53
	v_mov_b32_e32 v53, v54
	v_sub_f32_e32 v51, v51, v53
	v_mul_f32_e32 v60, 0x3f317217, v64
	v_fma_f32 v66, v64, s36, -v60
	v_fmac_f32_e32 v66, 0x3377d1cf, v64
	v_fmac_f32_e32 v66, 0x3f317217, v64
	v_mul_f32_e64 v52, |v151|, s4
	v_exp_f32_e32 v52, v52
	v_mov_b32_e32 v54, v66
	v_min_f32_e32 v53, 0, v151
	v_add_f32_e32 v52, 1.0, v52
	s_nop 1
	v_log_f32_e32 v66, v52
	v_mov_b32_e32 v52, v54
	v_sub_f32_e32 v52, v65, v52
	v_mul_f32_e32 v62, 0x3f317217, v66
	v_fma_f32 v67, v66, s36, -v62
	v_fmac_f32_e32 v67, 0x3377d1cf, v66
	v_fmac_f32_e32 v67, 0x3f317217, v66
	v_mul_f32_e64 v55, |v164|, s4
	v_exp_f32_e32 v55, v55
	s_nop 0
	v_add_f32_e32 v55, 1.0, v55
	v_mov_b32_e32 v56, v67
	v_min_f32_e32 v67, 0, v164
	v_log_f32_e32 v66, v55
	v_mov_b32_e32 v55, v56
	v_sub_f32_e32 v53, v53, v55
	v_mul_f32_e32 v62, 0x3f317217, v66
	v_fma_f32 v68, v66, s36, -v62
	v_fmac_f32_e32 v68, 0x3377d1cf, v66
	v_fmac_f32_e32 v68, 0x3f317217, v66
	v_mul_f32_e64 v54, |v165|, s4
	v_exp_f32_e32 v54, v54
	v_mov_b32_e32 v56, v68
	v_min_f32_e32 v55, 0, v165
	v_add_f32_e32 v54, 1.0, v54
	s_nop 1
	v_log_f32_e32 v68, v54
	v_mov_b32_e32 v54, v56
	v_sub_f32_e32 v54, v67, v54
	v_mul_f32_e32 v64, 0x3f317217, v68
	v_fma_f32 v69, v68, s36, -v64
	v_fmac_f32_e32 v69, 0x3377d1cf, v68
	v_fmac_f32_e32 v69, 0x3f317217, v68
	v_mul_f32_e64 v57, |v166|, s4
	v_exp_f32_e32 v57, v57
	s_nop 0
	v_add_f32_e32 v57, 1.0, v57
	v_mov_b32_e32 v58, v69
	v_min_f32_e32 v69, 0, v166
	v_log_f32_e32 v68, v57
	v_mov_b32_e32 v57, v58
	v_sub_f32_e32 v55, v55, v57
	v_mul_f32_e32 v64, 0x3f317217, v68
	v_fma_f32 v70, v68, s36, -v64
	v_fmac_f32_e32 v70, 0x3377d1cf, v68
	v_fmac_f32_e32 v70, 0x3f317217, v68
	v_mul_f32_e64 v56, |v167|, s4
	v_exp_f32_e32 v56, v56
	v_mov_b32_e32 v58, v70
	v_min_f32_e32 v57, 0, v167
	v_add_f32_e32 v56, 1.0, v56
	s_nop 1
	v_log_f32_e32 v70, v56
	v_mov_b32_e32 v56, v58
	v_sub_f32_e32 v56, v69, v56
	v_mul_f32_e32 v66, 0x3f317217, v70
	v_fma_f32 v71, v70, s36, -v66
	v_fmac_f32_e32 v71, 0x3377d1cf, v70
	v_fmac_f32_e32 v71, 0x3f317217, v70
	v_mul_f32_e64 v59, |v152|, s4
	v_exp_f32_e32 v59, v59
	s_nop 0
	v_add_f32_e32 v59, 1.0, v59
	v_mov_b32_e32 v60, v71
	v_min_f32_e32 v71, 0, v152
	v_log_f32_e32 v70, v59
	v_mov_b32_e32 v59, v60
	v_sub_f32_e32 v57, v57, v59
	v_mul_f32_e32 v66, 0x3f317217, v70
	v_fma_f32 v72, v70, s36, -v66
	v_fmac_f32_e32 v72, 0x3377d1cf, v70
	v_fmac_f32_e32 v72, 0x3f317217, v70
	v_mul_f32_e64 v58, |v153|, s4
	v_exp_f32_e32 v58, v58
	v_mov_b32_e32 v60, v72
	v_min_f32_e32 v59, 0, v153
	v_add_f32_e32 v58, 1.0, v58
	s_nop 1
	v_log_f32_e32 v72, v58
	v_mov_b32_e32 v58, v60
	v_sub_f32_e32 v58, v71, v58
	v_mul_f32_e32 v68, 0x3f317217, v72
	v_fma_f32 v73, v72, s36, -v68
	v_fmac_f32_e32 v73, 0x3377d1cf, v72
	v_fmac_f32_e32 v73, 0x3f317217, v72
	v_mul_f32_e64 v61, |v154|, s4
	v_exp_f32_e32 v61, v61
	s_nop 0
; __device__ __forceinline__ void gla_bcum(KArgs a, int tid, int t0, int h, LAS float* segtot, LAS float* glrs, float (&bc)[32], float& tot) {
;     ...
;         const float la = (fminf(z, 0.f) - __logf(1.0f + __expf(-fabsf(z)))) * (1.0f / 16.0f);
;         run += la; bc[r] = run; }
;     segtot[seg * 128 + d] = run;
;     __syncthreads();
	v_add_f32_e32 v61, 1.0, v61
	v_mov_b32_e32 v62, v73
	v_min_f32_e32 v73, 0, v154
	v_log_f32_e32 v72, v61
	v_mov_b32_e32 v61, v62
	v_sub_f32_e32 v59, v59, v61
	v_mul_f32_e32 v68, 0x3f317217, v72
	v_fma_f32 v74, v72, s36, -v68
	v_fmac_f32_e32 v74, 0x3377d1cf, v72
	v_fmac_f32_e32 v74, 0x3f317217, v72
	v_mul_f32_e64 v60, |v155|, s4
	v_exp_f32_e32 v60, v60
	v_mov_b32_e32 v62, v74
	v_min_f32_e32 v61, 0, v155
	v_add_f32_e32 v60, 1.0, v60
	s_nop 1
	v_log_f32_e32 v74, v60
	v_mov_b32_e32 v60, v62
	v_sub_f32_e32 v60, v73, v60
	v_mul_f32_e32 v70, 0x3f317217, v74
	v_fma_f32 v75, v74, s36, -v70
	v_fmac_f32_e32 v75, 0x3377d1cf, v74
	v_fmac_f32_e32 v75, 0x3f317217, v74
	v_mul_f32_e64 v63, |v168|, s4
	v_exp_f32_e32 v63, v63
	s_nop 0
	v_add_f32_e32 v63, 1.0, v63
	v_mov_b32_e32 v64, v75
	v_min_f32_e32 v75, 0, v168
	v_log_f32_e32 v74, v63
	v_mov_b32_e32 v63, v64
	v_sub_f32_e32 v61, v61, v63
	v_mul_f32_e32 v70, 0x3f317217, v74
	v_fma_f32 v76, v74, s36, -v70
	v_fmac_f32_e32 v76, 0x3377d1cf, v74
	v_fmac_f32_e32 v76, 0x3f317217, v74
	v_mul_f32_e64 v62, |v169|, s4
	v_exp_f32_e32 v62, v62
	v_mov_b32_e32 v64, v76
	v_min_f32_e32 v63, 0, v169
	v_add_f32_e32 v62, 1.0, v62
	s_nop 1
	v_log_f32_e32 v76, v62
	v_mov_b32_e32 v62, v64
	v_sub_f32_e32 v62, v75, v62
	v_mul_f32_e32 v72, 0x3f317217, v76
	v_fma_f32 v77, v76, s36, -v72
	v_fmac_f32_e32 v77, 0x3377d1cf, v76
	v_fmac_f32_e32 v77, 0x3f317217, v76
	v_mul_f32_e64 v65, |v170|, s4
	v_exp_f32_e32 v65, v65
	s_nop 0
	v_add_f32_e32 v65, 1.0, v65
	v_mov_b32_e32 v66, v77
	v_min_f32_e32 v77, 0, v170
	v_log_f32_e32 v76, v65
	v_mov_b32_e32 v65, v66
	v_sub_f32_e32 v63, v63, v65
	v_mul_f32_e32 v72, 0x3f317217, v76
	v_fma_f32 v78, v76, s36, -v72
	v_fmac_f32_e32 v78, 0x3377d1cf, v76
	v_fmac_f32_e32 v78, 0x3f317217, v76
	v_mul_f32_e64 v64, |v171|, s4
	v_exp_f32_e32 v64, v64
	v_mov_b32_e32 v66, v78
	v_min_f32_e32 v65, 0, v171
	v_add_f32_e32 v64, 1.0, v64
	s_nop 1
	v_log_f32_e32 v78, v64
	v_mov_b32_e32 v64, v66
	v_sub_f32_e32 v64, v77, v64
	v_mul_f32_e32 v74, 0x3f317217, v78
	v_fma_f32 v79, v78, s36, -v74
	v_fmac_f32_e32 v79, 0x3377d1cf, v78
	v_fmac_f32_e32 v79, 0x3f317217, v78
	v_mul_f32_e64 v67, |v156|, s4
	v_exp_f32_e32 v67, v67
	s_nop 0
	v_add_f32_e32 v67, 1.0, v67
	v_mov_b32_e32 v68, v79
	v_min_f32_e32 v79, 0, v156
	v_log_f32_e32 v78, v67
	v_mov_b32_e32 v67, v68
	v_sub_f32_e32 v65, v65, v67
	v_mul_f32_e32 v74, 0x3f317217, v78
	v_fma_f32 v80, v78, s36, -v74
	v_fmac_f32_e32 v80, 0x3377d1cf, v78
	v_fmac_f32_e32 v80, 0x3f317217, v78
	v_mul_f32_e64 v67, |v157|, s4
	v_exp_f32_e32 v67, v67
	v_mov_b32_e32 v68, v80
	v_min_f32_e32 v80, 0, v157
	v_add_f32_e32 v67, 1.0, v67
	s_nop 1
	v_log_f32_e32 v78, v67
	v_mov_b32_e32 v67, v68
	v_sub_f32_e32 v79, v79, v67
	v_mul_f32_e32 v74, 0x3f317217, v78
	v_fma_f32 v81, v78, s36, -v74
	v_fmac_f32_e32 v81, 0x3377d1cf, v78
	v_fmac_f32_e32 v81, 0x3f317217, v78
	v_mul_f32_e64 v67, |v158|, s4
	v_exp_f32_e32 v67, v67
	v_mov_b32_e32 v68, v81
	v_min_f32_e32 v81, 0, v158
	v_add_f32_e32 v67, 1.0, v67
	s_nop 1
	v_log_f32_e32 v78, v67
	v_mov_b32_e32 v67, v68
	v_sub_f32_e32 v80, v80, v67
	v_mul_f32_e32 v74, 0x3f317217, v78
	v_fma_f32 v82, v78, s36, -v74
	v_fmac_f32_e32 v82, 0x3377d1cf, v78
	v_fmac_f32_e32 v82, 0x3f317217, v78
	v_mul_f32_e64 v67, |v159|, s4
	v_exp_f32_e32 v67, v67
	v_mov_b32_e32 v68, v82
	v_min_f32_e32 v82, 0, v159
	v_add_f32_e32 v67, 1.0, v67
	s_nop 1
	v_log_f32_e32 v78, v67
	v_mov_b32_e32 v67, v68
	v_sub_f32_e32 v81, v81, v67
	v_mul_f32_e32 v74, 0x3f317217, v78
	v_fma_f32 v83, v78, s36, -v74
	v_fmac_f32_e32 v83, 0x3377d1cf, v78
	v_fmac_f32_e32 v83, 0x3f317217, v78
	v_mul_f32_e64 v67, |v172|, s4
	v_exp_f32_e32 v67, v67
	v_mov_b32_e32 v68, v83
	v_min_f32_e32 v83, 0, v172
	v_add_f32_e32 v67, 1.0, v67
	s_nop 1
	v_log_f32_e32 v78, v67
	v_mov_b32_e32 v67, v68
	v_sub_f32_e32 v82, v82, v67
	v_mul_f32_e32 v74, 0x3f317217, v78
	v_fma_f32 v84, v78, s36, -v74
	v_fmac_f32_e32 v84, 0x3377d1cf, v78
	v_fmac_f32_e32 v84, 0x3f317217, v78
	v_mul_f32_e64 v67, |v173|, s4
	v_exp_f32_e32 v67, v67
	v_mov_b32_e32 v68, v84
	v_min_f32_e32 v84, 0, v173
	v_add_f32_e32 v67, 1.0, v67
	s_nop 1
	v_log_f32_e32 v78, v67
	v_mov_b32_e32 v67, v68
	v_sub_f32_e32 v83, v83, v67
	v_mul_f32_e32 v74, 0x3f317217, v78
	v_fma_f32 v85, v78, s36, -v74
	v_fmac_f32_e32 v85, 0x3377d1cf, v78
	v_fmac_f32_e32 v85, 0x3f317217, v78
	v_mul_f32_e64 v67, |v174|, s4
	v_exp_f32_e32 v67, v67
	v_mov_b32_e32 v68, v85
	v_min_f32_e32 v78, 0, v174
	v_add_f32_e32 v67, 1.0, v67
	s_nop 1
	v_log_f32_e32 v76, v67
	v_mov_b32_e32 v67, v68
	v_sub_f32_e32 v77, v84, v67
	v_mul_f32_e32 v74, 0x3f317217, v76
	v_fma_f32 v84, v76, s36, -v74
	v_fmac_f32_e32 v84, 0x3377d1cf, v76
	v_fmac_f32_e32 v84, 0x3f317217, v76
	s_nop 0
	v_mul_f32_e64 v14, |v175|, s4
	v_exp_f32_e32 v14, v14
	v_mov_b32_e32 v15, v84
	v_sub_f32_e32 v15, v78, v15
	v_add_f32_e32 v14, 1.0, v14
	v_min_f32_e32 v2, 0, v175
	s_nop 0
	v_fmamk_f32 v17, v49, 0x3d800000, v48
	v_fmamk_f32 v42, v50, 0x3d800000, v17
	v_fmamk_f32 v49, v51, 0x3d800000, v42
	v_fmamk_f32 v66, v52, 0x3d800000, v49
	v_fmamk_f32 v67, v53, 0x3d800000, v66
	v_fmamk_f32 v68, v54, 0x3d800000, v67
	v_fmamk_f32 v69, v55, 0x3d800000, v68
	v_fmamk_f32 v70, v56, 0x3d800000, v69
	v_fmamk_f32 v71, v57, 0x3d800000, v70
	v_fmamk_f32 v58, v58, 0x3d800000, v71
	v_fmamk_f32 v59, v59, 0x3d800000, v58
	v_fmamk_f32 v60, v60, 0x3d800000, v59
	v_fmamk_f32 v61, v61, 0x3d800000, v60
	v_log_f32_e32 v14, v14
	v_fmamk_f32 v62, v62, 0x3d800000, v61
	v_fmamk_f32 v63, v63, 0x3d800000, v62
	v_fmamk_f32 v64, v64, 0x3d800000, v63
	v_fmamk_f32 v65, v65, 0x3d800000, v64
	v_mul_f32_e32 v16, 0x3f317217, v14
	v_fmamk_f32 v72, v79, 0x3d800000, v65
	v_fma_f32 v16, v14, s36, -v16
	v_fmamk_f32 v73, v80, 0x3d800000, v72
	v_fmac_f32_e32 v16, 0x3377d1cf, v14
	v_fmamk_f32 v74, v81, 0x3d800000, v73
	v_fmac_f32_e32 v16, 0x3f317217, v14
	v_fmamk_f32 v75, v82, 0x3d800000, v74
	v_fmamk_f32 v76, v83, 0x3d800000, v75
	v_mov_b32_e32 v14, v16
	v_fmamk_f32 v77, v77, 0x3d800000, v76
	v_sub_f32_e32 v2, v2, v14
	v_fmamk_f32 v78, v15, 0x3d800000, v77
	v_lshl_add_u32 v14, s1, 2, v34
	v_fmamk_f32 v79, v2, 0x3d800000, v78
	ds_write_b32 v14, v79
	s_waitcnt lgkmcnt(0)
	s_barrier
; #define LAS __attribute__((address_space(3)))
; __device__ __forceinline__ float bf2f(bf16_t v) { return __uint_as_float((unsigned)v << 16); }
; #define X make_ctx(lds_raw)
; __device__ __forceinline__ void gla_bcum(KArgs a, int tid, int t0, int h, LAS float* segtot, LAS float* glrs, float (&bc)[32], float& tot) {
;     ...
;     float off = 0.f; tot = 0.f;
; #pragma unroll
;     for (int s2 = 0; s2 < 4; ++s2) { const float v = segtot[s2 * 128 + d]; tot += v; if (s2 < seg) off += v; }
; #pragma unroll
;     for (int r = 0; r < 32; ++r) bc[r] += off;
; }
; __device__ __forceinline__ void gla_stage_vT(const bf16_t* proj, int tid, int t0, int h, LAS bf16_t* vT) {
; #pragma unroll
;     for (int q = 0; q < 8; ++q) { const int i = tid >> 2, c = (tid & 3) + 4 * q;
;         const u32x4 wv = *(const u32x4*)(proj + (size_t)(t0 + i) * NMAIN + C_GV + h * 256 + 8 * c);
;         LAS bf16_t* vp = vT + (8 * c) * GP + i;
;         vp[0 * GP] = (bf16_t)(wv.x & 0xffff); vp[1 * GP] = (bf16_t)(wv.x >> 16); vp[2 * GP] = (bf16_t)(wv.y & 0xffff); vp[3 * GP] = (bf16_t)(wv.y >> 16);
;         vp[4 * GP] = (bf16_t)(wv.z & 0xffff); vp[5 * GP] = (bf16_t)(wv.z >> 16); vp[6 * GP] = (bf16_t)(wv.w & 0xffff); vp[7 * GP] = (bf16_t)(wv.w >> 16); }
; }
; __device__ __forceinline__ void gla_a1(const Ctx& X, KArgs a, float* kvt, float* decb) {
;     const bf16_t* proj = (const bf16_t*)(a->ws + WS_BIG);
;     LAS bf16_t* kdT = (LAS bf16_t*)X.lds; LAS bf16_t* vT = (LAS bf16_t*)(X.lds + 128 * GP * 2); LAS float* segtot = (LAS float*)(X.lds + 384 * GP * 2);
;     const int fr = X.lane & 15, fq = X.lane >> 4, w = X.wave;
;     for (int unit = blockIdx.x; unit < 512; unit += gridDim.x) {
;         const int bh = unit >> 5, n = unit & 31, b = bh >> 2, h = bh & 3, t0 = b * SEQ + n * 128;
;         __syncthreads();
;         float bc[32], tot; gla_bcum(a, X.tid, t0, h, segtot, (LAS float*)vT, bc, tot);
;         { const int d = X.tid & 127, seg = X.tid >> 7;
; #pragma unroll
;           for (int r8 = 0; r8 < 4; ++r8) { float kd[8];
; #pragma unroll
;               for (int e = 0; e < 8; ++e) { const int r = r8 * 8 + e; kd[e] = bf2f(proj[(size_t)(t0 + seg * 32 + r) * NMAIN + C_GK + h * 128 + d]) * __expf(tot - bc[r]); }
;               *(LAS u32x4*)(kdT + d * GP + seg * 32 + r8 * 8) = pack8(kd); }
	ds_read2st64_b32 v[14:15], v34 offset1:2
	ds_read2st64_b32 v[20:21], v34 offset0:4 offset1:6
	s_cselect_b64 s[6:7], -1, 0
	s_cmp_gt_i32 s0, 1
	s_waitcnt lgkmcnt(1)
	v_add_f32_e32 v2, 0, v14
	v_cndmask_b32_e64 v14, 0, v2, s[6:7]
	v_add_f32_e32 v16, v15, v14
	s_cselect_b64 s[6:7], -1, 0
	s_cmp_gt_i32 s0, 2
	v_cndmask_b32_e64 v14, v14, v16, s[6:7]
	s_waitcnt lgkmcnt(0)
	v_add_f32_e32 v18, v20, v14
	s_cselect_b64 s[6:7], -1, 0
	v_add_f32_e32 v2, v15, v2
	s_cmp_gt_i32 s0, 3
	v_add_f32_e32 v16, v20, v2
	v_cndmask_b32_e64 v2, v14, v18, s[6:7]
	v_add_f32_e32 v14, v21, v2
	s_cselect_b64 s[6:7], -1, 0
	v_cndmask_b32_e64 v19, v2, v14, s[6:7]
	s_nop 0
	s_nop 0
	s_nop 0
	v_mov_b32_e32 v18, v21
	v_add_f32_e32 v13, v13, v19
	v_pk_add_f32 v[16:17], v[18:19], v[16:17]
	v_add_f32_e32 v44, v44, v19
	v_add_f32_e32 v46, v46, v19
	v_sub_f32_e32 v13, v16, v13
	v_add_f32_e32 v25, v43, v19
	v_add_f32_e32 v26, v45, v19
	v_add_f32_e32 v27, v47, v19
	v_add_f32_e32 v28, v48, v19
	v_add_f32_e32 v21, v42, v19
	v_add_f32_e32 v42, v49, v19
	v_add_f32_e32 v43, v66, v19
	v_add_f32_e32 v55, v67, v19
	v_add_f32_e32 v56, v68, v19
	v_add_f32_e32 v57, v69, v19
	v_add_f32_e32 v66, v70, v19
	v_add_f32_e32 v67, v71, v19
	v_add_f32_e32 v58, v58, v19
	v_add_f32_e32 v59, v59, v19
	v_add_f32_e32 v60, v60, v19
	v_add_f32_e32 v61, v61, v19
	v_add_f32_e32 v62, v62, v19
	v_add_f32_e32 v63, v63, v19
	v_add_f32_e32 v64, v64, v19
	v_add_f32_e32 v65, v65, v19
	v_add_f32_e32 v68, v72, v19
	v_add_f32_e32 v69, v73, v19
	v_add_f32_e32 v70, v74, v19
	v_add_f32_e32 v71, v75, v19
	v_add_f32_e32 v72, v76, v19
	v_add_f32_e32 v73, v77, v19
	v_add_f32_e32 v74, v78, v19
	v_add_f32_e32 v75, v19, v79
	v_sub_f32_e32 v18, v16, v44
	v_sub_f32_e32 v19, v16, v46
	v_mul_f32_e32 v13, 0x3fb8aa3b, v13
	v_mul_f32_e32 v18, 0x3fb8aa3b, v18
	v_mul_f32_e32 v19, 0x3fb8aa3b, v19
	v_exp_f32_e32 v24, v13
	v_sub_f32_e32 v13, v16, v25
	v_exp_f32_e32 v18, v18
	v_exp_f32_e32 v19, v19
	v_mul_f32_e32 v13, 0x3fb8aa3b, v13
	v_exp_f32_e32 v25, v13
	s_waitcnt vmcnt(30)
	v_lshlrev_b32_e32 v23, 16, v193
	v_lshlrev_b32_e32 v22, 16, v192
	v_sub_f32_e32 v13, v16, v26
	v_pk_mul_f32 v[18:19], v[18:19], v[22:23]
	s_waitcnt vmcnt(28)
	v_lshlrev_b32_e32 v23, 16, v195
	v_lshlrev_b32_e32 v22, 16, v194
	v_mul_f32_e32 v13, 0x3fb8aa3b, v13
	v_pk_mul_f32 v[24:25], v[24:25], v[22:23]
	v_exp_f32_e32 v22, v13
	v_sub_f32_e32 v13, v16, v27
	v_mul_f32_e32 v13, 0x3fb8aa3b, v13
	v_exp_f32_e32 v23, v13
	v_sub_f32_e32 v13, v16, v28
	v_mul_f32_e32 v13, 0x3fb8aa3b, v13
	v_exp_f32_e32 v28, v13
	v_sub_f32_e32 v13, v16, v17
	v_mul_f32_e32 v13, 0x3fb8aa3b, v13
	v_exp_f32_e32 v29, v13
	s_waitcnt vmcnt(26)
	v_lshlrev_b32_e32 v27, 16, v197
	v_lshlrev_b32_e32 v26, 16, v196
	v_pk_mul_f32 v[26:27], v[22:23], v[26:27]
	s_waitcnt vmcnt(24)
	v_lshlrev_b32_e32 v23, 16, v199
	v_lshlrev_b32_e32 v22, 16, v198
	v_pk_mul_f32 v[28:29], v[28:29], v[22:23]
	v_cvt_pk_bf16_f32 v22, v18, v19
	v_cvt_pk_bf16_f32 v23, v24, v25
	v_cvt_pk_bf16_f32 v24, v26, v27
	v_cvt_pk_bf16_f32 v25, v28, v29
	v_sub_f32_e32 v13, v16, v21
	ds_write_b128 v37, v[22:25]
	v_mul_f32_e32 v13, 0x3fb8aa3b, v13
	v_exp_f32_e32 v18, v13
	v_sub_f32_e32 v13, v16, v42
	v_mul_f32_e32 v13, 0x3fb8aa3b, v13
	v_exp_f32_e32 v19, v13
	v_sub_f32_e32 v13, v16, v43
	s_waitcnt vmcnt(23)
	v_lshlrev_b32_e32 v22, 16, v200
	s_nop 0
	s_nop 0
	s_nop 0
	s_nop 0
	v_mul_f32_e32 v13, 0x3fb8aa3b, v13
	v_exp_f32_e32 v14, v13
	v_sub_f32_e32 v13, v16, v55
	v_mul_f32_e32 v13, 0x3fb8aa3b, v13
	v_exp_f32_e32 v15, v13
	v_sub_f32_e32 v13, v16, v56
	s_waitcnt vmcnt(20)
; #define LAS __attribute__((address_space(3)))
; __device__ __forceinline__ float bf2f(bf16_t v) { return __uint_as_float((unsigned)v << 16); }
; __device__ __forceinline__ u32x4 pack8(const float* f) { u32x4 w; w.x = pk2(f[0], f[1]); w.y = pk2(f[2], f[3]); w.z = pk2(f[4], f[5]); w.w = pk2(f[6], f[7]); return w; }
; __device__ __forceinline__ void gla_a1(const Ctx& X, KArgs a, float* kvt, float* decb) {
;     ...
;           for (int r8 = 0; r8 < 4; ++r8) { float kd[8];
; #pragma unroll
;               for (int e = 0; e < 8; ++e) { const int r = r8 * 8 + e; kd[e] = bf2f(proj[(size_t)(t0 + seg * 32 + r) * NMAIN + C_GK + h * 128 + d]) * __expf(tot - bc[r]); }
;               *(LAS u32x4*)(kdT + d * GP + seg * 32 + r8 * 8) = pack8(kd); }
;           if (seg == 0) decb[unit * 128 + d] = __expf(tot); }
	v_lshlrev_b32_e32 v21, 16, v203
	v_lshlrev_b32_e32 v20, 16, v202
	v_mul_f32_e32 v13, 0x3fb8aa3b, v13
	v_pk_mul_f32 v[14:15], v[14:15], v[20:21]
	v_exp_f32_e32 v20, v13
	v_sub_f32_e32 v13, v16, v57
	v_mul_f32_e32 v13, 0x3fb8aa3b, v13
	v_exp_f32_e32 v21, v13
	v_sub_f32_e32 v13, v16, v66
	v_mul_f32_e32 v13, 0x3fb8aa3b, v13
	v_exp_f32_e32 v24, v13
	v_sub_f32_e32 v13, v16, v67
	v_mul_f32_e32 v13, 0x3fb8aa3b, v13
	v_lshlrev_b32_e32 v23, 16, v201
	v_exp_f32_e32 v25, v13
	v_sub_f32_e32 v13, v16, v58
	v_pk_mul_f32 v[18:19], v[18:19], v[22:23]
	v_mul_f32_e32 v13, 0x3fb8aa3b, v13
	s_waitcnt vmcnt(18)
	v_lshlrev_b32_e32 v23, 16, v205
	v_lshlrev_b32_e32 v22, 16, v204
	v_cvt_pk_bf16_f32 v18, v18, v19
	v_cvt_pk_bf16_f32 v19, v14, v15
	v_exp_f32_e32 v14, v13
	v_sub_f32_e32 v13, v16, v59
	v_pk_mul_f32 v[20:21], v[20:21], v[22:23]
	s_waitcnt vmcnt(16)
	v_lshlrev_b32_e32 v23, 16, v207
	v_lshlrev_b32_e32 v22, 16, v206
	v_mul_f32_e32 v13, 0x3fb8aa3b, v13
	v_pk_mul_f32 v[22:23], v[24:25], v[22:23]
	v_exp_f32_e32 v15, v13
	v_sub_f32_e32 v13, v16, v60
	v_cvt_pk_bf16_f32 v20, v20, v21
	v_cvt_pk_bf16_f32 v21, v22, v23
	v_mul_f32_e32 v13, 0x3fb8aa3b, v13
	ds_write_b128 v37, v[18:21] offset:16
	v_exp_f32_e32 v20, v13
	v_sub_f32_e32 v13, v16, v61
	v_mul_f32_e32 v13, 0x3fb8aa3b, v13
	v_exp_f32_e32 v21, v13
	s_waitcnt vmcnt(14)
	v_lshlrev_b32_e32 v19, 16, v209
	v_lshlrev_b32_e32 v18, 16, v208
	v_sub_f32_e32 v13, v16, v62
	v_pk_mul_f32 v[14:15], v[14:15], v[18:19]
	s_waitcnt vmcnt(12)
	v_lshlrev_b32_e32 v19, 16, v211
	v_lshlrev_b32_e32 v18, 16, v210
	v_mul_f32_e32 v13, 0x3fb8aa3b, v13
	v_pk_mul_f32 v[20:21], v[20:21], v[18:19]
	v_exp_f32_e32 v18, v13
	v_sub_f32_e32 v13, v16, v63
	v_mul_f32_e32 v13, 0x3fb8aa3b, v13
	v_exp_f32_e32 v19, v13
	v_sub_f32_e32 v13, v16, v64
	v_mul_f32_e32 v13, 0x3fb8aa3b, v13
	v_exp_f32_e32 v24, v13
	v_sub_f32_e32 v13, v16, v65
	v_mul_f32_e32 v13, 0x3fb8aa3b, v13
	v_exp_f32_e32 v25, v13
	s_waitcnt vmcnt(10)
	v_lshlrev_b32_e32 v23, 16, v213
	v_lshlrev_b32_e32 v22, 16, v212
	v_pk_mul_f32 v[22:23], v[18:19], v[22:23]
	s_waitcnt vmcnt(8)
	v_lshlrev_b32_e32 v19, 16, v215
	v_lshlrev_b32_e32 v18, 16, v214
	v_pk_mul_f32 v[24:25], v[24:25], v[18:19]
	v_cvt_pk_bf16_f32 v18, v14, v15
	v_cvt_pk_bf16_f32 v19, v20, v21
	v_cvt_pk_bf16_f32 v20, v22, v23
	v_cvt_pk_bf16_f32 v21, v24, v25
	v_sub_f32_e32 v13, v16, v68
	ds_write_b128 v37, v[18:21] offset:32
	v_mul_f32_e32 v13, 0x3fb8aa3b, v13
	s_waitcnt vmcnt(6)
	v_lshlrev_b32_e32 v19, 16, v217
	v_sub_f32_e32 v2, v16, v70
	v_exp_f32_e32 v14, v13
	v_sub_f32_e32 v13, v16, v69
	v_mul_f32_e32 v2, 0x3fb8aa3b, v2
	v_mul_f32_e32 v13, 0x3fb8aa3b, v13
	v_exp_f32_e32 v20, v2
	v_sub_f32_e32 v2, v16, v71
	v_exp_f32_e32 v15, v13
	v_mul_f32_e32 v2, 0x3fb8aa3b, v2
	v_exp_f32_e32 v21, v2
	v_lshlrev_b32_e32 v18, 16, v216
	v_sub_f32_e32 v2, v16, v72
	v_pk_mul_f32 v[14:15], v[14:15], v[18:19]
	s_waitcnt vmcnt(4)
	v_lshlrev_b32_e32 v19, 16, v219
	v_lshlrev_b32_e32 v18, 16, v218
	v_mul_f32_e32 v2, 0x3fb8aa3b, v2
	v_pk_mul_f32 v[20:21], v[20:21], v[18:19]
	v_exp_f32_e32 v18, v2
	v_sub_f32_e32 v2, v16, v73
	v_mul_f32_e32 v2, 0x3fb8aa3b, v2
	v_exp_f32_e32 v19, v2
	v_sub_f32_e32 v2, v16, v74
	v_mul_f32_e32 v2, 0x3fb8aa3b, v2
	v_exp_f32_e32 v24, v2
	v_sub_f32_e32 v2, v16, v75
	v_mul_f32_e32 v2, 0x3fb8aa3b, v2
	v_exp_f32_e32 v25, v2
	s_waitcnt vmcnt(2)
	v_lshlrev_b32_e32 v23, 16, v221
	v_lshlrev_b32_e32 v22, 16, v220
	v_pk_mul_f32 v[22:23], v[18:19], v[22:23]
	s_waitcnt vmcnt(0)
	v_lshlrev_b32_e32 v19, 16, v223
	v_lshlrev_b32_e32 v18, 16, v222
	v_pk_mul_f32 v[24:25], v[24:25], v[18:19]
	v_cvt_pk_bf16_f32 v18, v14, v15
	v_cvt_pk_bf16_f32 v19, v20, v21
	v_cvt_pk_bf16_f32 v20, v22, v23
	v_cvt_pk_bf16_f32 v21, v24, v25
	ds_write_b128 v37, v[18:21] offset:48
	s_and_saveexec_b64 s[0:1], vcc
	s_cbranch_execz .LBB0_340
	v_mul_f32_e32 v2, 0x3fb8aa3b, v16
	v_exp_f32_e32 v2, v2
	v_add_u32_e32 v14, s3, v32
	v_ashrrev_i32_e32 v15, 31, v14
	v_lshl_add_u64 v[14:15], v[14:15], 2, s[16:17]
	global_store_dword v[14:15], v2, off
	s_branch .LBB0_340
